# MLA attention loop (layer 0): removed 8 loop-invariant v_readlane SGPR reloads per iteration
# speedup vs baseline: 1.0086x; 1.0082x over previous
; template <int MODE>
; DI void attn_unit(char* lds, const Params& p, int layer, int u) {
;     ...
;     char* cur = lds + (t & 1) * BUFSZ;
;     if (t + 1 < NT) { stage(lds + ((t + 1) & 1) * BUFSZ); if (t + 2 < NT) prefetch(t + 2); }
;     const int key0 = (MODE == 3) ? q0 - 64 + 64 * t : 64 * (tlo + t);
;     const bool act = (MODE != 3) || (t >= (wid >> 1) && t <= (wid >> 1) + 2);
;     if (act) {
;       f32x16 S0 = zero16(), S1 = zero16();
;       const char* kb = cur + lr * KST + (MODE == 0 ? comp * 64 : 0) + lh * 16;
; #pragma unroll
;       for (int ks = 0; ks < NKS; ++ks) {
;         const bf16x8 k0 = *(const bf16x8*)(kb + ks * 32), k1 = *(const bf16x8*)(kb + 32 * KST + ks * 32);
;         S0 = mfma32(k0, qf[ks], S0); S1 = mfma32(k1, qf[ks], S1);
;       }
;       float aoff = 0.f;
;       if (MODE == 0) {
;         const float dbase = (float)(key0 + 4 * lh - qrow);
;         if (key0 > qlo + 31) { S0 = S0 - T0; S1 = S1 - T1; aoff = -slope2 * dbase; }
;         else if (key0 + 63 < qlo) { S0 = S0 + T0; S1 = S1 + T1; aoff = slope2 * dbase; }
;         else {
; #pragma unroll
;           for (int r = 0; r < 16; ++r) { const float cc = (float)((r & 3) + 8 * (r >> 2));
;             S0[r] = fmaf(-slope2, fabsf(dbase + cc), S0[r]); S1[r] = fmaf(-slope2, fabsf(dbase + cc + 32.f), S1[r]); }
;         }
;       }
;       if (MODE == 3) {
;         const int rel0 = key0 + 4 * lh - qrow;
; #pragma unroll
;         for (int r = 0; r < 16; ++r) { const int cc = (r & 3) + 8 * (r >> 2);
;           { const int rel = rel0 + cc, v = qrow + rel; const bool ok = (rel >= -64) && (rel <= 64) && (v >= 0) && (v < L); S0[r] = ok ? fmaf(-slope2, fabsf((float)rel), S0[r]) : -1e30f; }
;           { const int rel = rel0 + cc + 32, v = qrow + rel; const bool ok = (rel >= -64) && (rel <= 64) && (v >= 0) && (v < L); S1[r] = ok ? fmaf(-slope2, fabsf((float)rel), S1[r]) : -1e30f; } }
;       }
;       float mx = fmaxf(S0[0], S1[0]);
; #pragma unroll
;       for (int r = 1; r < 16; ++r) mx = max3f(mx, S0[r], S1[r]);
;       mx += aoff;
;       if (__any(mx > m + 8.f)) {
;         mx = fmaxf(mx, __shfl_xor(mx, 32));
;         const float mnew = fmaxf(m, mx);
;         const float al = __builtin_amdgcn_exp2f(m - mnew); l *= al; O0 *= al; O1 *= al;
;         m = mnew;
;       }
.LBB0_600:
	s_or_b64 exec, exec, s[66:67]
	s_cmp_eq_u32 s50, 1
	s_cselect_b32 s50, 0, 0x5800
	v_add3_u32 v32, s51, v123, v108
	s_waitcnt vmcnt(0)
	ds_write_b128 v32, v[92:95] offset:13312
	v_add3_u32 v104, s50, v103, v106
	ds_read_b128 v[32:35], v104
	ds_read_b128 v[88:91], v104 offset:32
	ds_read_b128 v[48:51], v104 offset:6656
	v_readlane_b32 s52, v252, 0
	v_readlane_b32 s60, v252, 8
	v_readlane_b32 s61, v252, 9
	v_readlane_b32 s53, v252, 1
	s_waitcnt lgkmcnt(2)
	v_mfma_f32_32x32x16_bf16 v[32:47], v[32:35], v[84:87], 0
	v_mov_b64_e32 v[92:93], s[60:61]
	v_mad_i64_i32 v[92:93], s[52:53], v116, s72, v[92:93]
	v_ashrrev_i32_e32 v117, 31, v116
	v_lshl_add_u64 v[92:93], v[92:93], 0, v[112:113]
	v_add_co_u32_e32 v92, vcc, s74, v92
	s_waitcnt lgkmcnt(1)
	v_mfma_f32_32x32x16_bf16 v[32:47], v[88:91], v[80:83], v[32:47]
	ds_read_b128 v[88:91], v104 offset:6688
	v_addc_co_u32_e32 v93, vcc, 0, v93, vcc
	s_waitcnt lgkmcnt(1)
	v_mfma_f32_32x32x16_bf16 v[48:63], v[48:51], v[84:87], 0
	v_readlane_b32 s64, v252, 12
	v_readlane_b32 s65, v252, 13
	v_readlane_b32 s66, v252, 14
	s_waitcnt lgkmcnt(0)
	v_mfma_f32_32x32x16_bf16 v[48:63], v[88:91], v[80:83], v[48:63]
	ds_read_b128 v[88:91], v104 offset:64
	v_readlane_b32 s67, v252, 15
	s_waitcnt lgkmcnt(0)
	v_mfma_f32_32x32x16_bf16 v[32:47], v[88:91], v[76:79], v[32:47]
	ds_read_b128 v[88:91], v104 offset:6720
	ds_read_b128 v[126:129], v104 offset:96
	s_waitcnt lgkmcnt(1)
	v_mfma_f32_32x32x16_bf16 v[48:63], v[88:91], v[76:79], v[48:63]
	v_lshlrev_b64 v[88:89], 9, v[116:117]
	v_lshl_add_u64 v[88:89], v[110:111], 0, v[88:89]
	global_load_dwordx4 v[88:91], v[88:89], off
	s_nop 0
	global_load_dwordx4 v[96:99], v[92:93], off offset:1280
	s_nop 0
	global_load_dwordx4 v[92:95], v[118:119], off
	s_waitcnt lgkmcnt(0)
	v_mfma_f32_32x32x16_bf16 v[32:47], v[126:129], v[72:75], v[32:47]
	ds_read_b128 v[126:129], v104 offset:6752
	s_waitcnt lgkmcnt(0)
	v_mfma_f32_32x32x16_bf16 v[48:63], v[126:129], v[72:75], v[48:63]
	ds_read_b128 v[126:129], v104 offset:128
	s_waitcnt lgkmcnt(0)
	v_mfma_f32_32x32x16_bf16 v[32:47], v[126:129], v[68:71], v[32:47]
	ds_read_b128 v[126:129], v104 offset:6784
	s_waitcnt lgkmcnt(0)
	v_mfma_f32_32x32x16_bf16 v[48:63], v[126:129], v[68:71], v[48:63]
	ds_read_b128 v[126:129], v104 offset:6816
	s_waitcnt lgkmcnt(0)
	v_mfma_f32_32x32x16_bf16 v[48:63], v[126:129], v[64:67], v[48:63]
	ds_read_b128 v[126:129], v104 offset:160
	s_waitcnt lgkmcnt(0)
	v_mfma_f32_32x32x16_bf16 v[32:47], v[126:129], v[64:67], v[32:47]
	s_nop 8
	v_max_f32_e32 v104, v48, v48
	s_nop 1
	v_max_f32_e32 v105, v32, v32
	v_max_f32_e32 v104, v105, v104
	v_max3_f32 v104, v104, v33, v49
	v_add_f32_e32 v105, 0x41000000, v107
	v_max3_f32 v104, v104, v34, v50
	v_max3_f32 v104, v104, v35, v51
	v_max3_f32 v104, v104, v36, v52
	v_max3_f32 v104, v104, v37, v53
	v_max3_f32 v104, v104, v38, v54
	v_max3_f32 v104, v104, v39, v55
	v_max3_f32 v104, v104, v40, v56
	v_max3_f32 v104, v104, v41, v57
	v_max3_f32 v104, v104, v42, v58
	v_max3_f32 v104, v104, v43, v59
	v_max3_f32 v104, v104, v44, v60
	v_max3_f32 v104, v104, v45, v61
	v_max3_f32 v104, v104, v46, v62
	v_max3_f32 v104, v104, v47, v63
	v_cmp_gt_f32_e32 vcc, v104, v105
	s_cbranch_vccz .LBB0_597
	v_cmp_lt_i32_e32 vcc, v209, v208
	v_add_f32_e32 v104, 0, v104
	s_nop 0
	v_cndmask_b32_e32 v105, v207, v209, vcc
	v_lshlrev_b32_e32 v105, 2, v105
	ds_bpermute_b32 v105, v105, v104
	s_waitcnt lgkmcnt(0)
	v_max3_f32 v105, v107, v104, v105
	v_sub_f32_e32 v104, v107, v105
	v_exp_f32_e32 v104, v104
	v_mov_b32_e32 v107, v105
	v_mul_f32_e32 v109, v109, v104
	v_pk_mul_f32 v[14:15], v[14:15], v[104:105] op_sel_hi:[1,0]
	v_pk_mul_f32 v[12:13], v[12:13], v[104:105] op_sel_hi:[1,0]
	v_pk_mul_f32 v[10:11], v[10:11], v[104:105] op_sel_hi:[1,0]
	v_pk_mul_f32 v[8:9], v[8:9], v[104:105] op_sel_hi:[1,0]
	v_pk_mul_f32 v[6:7], v[6:7], v[104:105] op_sel_hi:[1,0]
	v_pk_mul_f32 v[4:5], v[4:5], v[104:105] op_sel_hi:[1,0]
	v_pk_mul_f32 v[2:3], v[2:3], v[104:105] op_sel_hi:[1,0]
	v_pk_mul_f32 v[0:1], v[0:1], v[104:105] op_sel_hi:[1,0]
	v_pk_mul_f32 v[30:31], v[30:31], v[104:105] op_sel_hi:[1,0]
	v_pk_mul_f32 v[28:29], v[28:29], v[104:105] op_sel_hi:[1,0]
	v_pk_mul_f32 v[26:27], v[26:27], v[104:105] op_sel_hi:[1,0]
	v_pk_mul_f32 v[24:25], v[24:25], v[104:105] op_sel_hi:[1,0]
	v_pk_mul_f32 v[22:23], v[22:23], v[104:105] op_sel_hi:[1,0]
	v_pk_mul_f32 v[20:21], v[20:21], v[104:105] op_sel_hi:[1,0]
	v_pk_mul_f32 v[18:19], v[18:19], v[104:105] op_sel_hi:[1,0]
	v_pk_mul_f32 v[16:17], v[16:17], v[104:105] op_sel_hi:[1,0]
	s_branch .LBB0_597
